# nt (streaming) hint on the MLP-up output (U) stores; on top of eb6
# baseline (speedup 1.0000x reference)
.LBB0_1545:
	v_lshl_add_u32 v136, s46, 8, v0
	v_max_f32_e32 v126, v126, v126
	v_ashrrev_i32_e32 v137, 31, v136
	v_max_f32_e32 v126, 0, v126
	v_max_f32_e32 v127, v127, v127
	v_max_f32_e32 v128, v128, v128
	v_lshl_or_b32 v134, s67, 8, v17
	v_lshlrev_b64 v[138:139], 14, v[136:137]
	v_mul_f32_e32 v137, v126, v126
	v_max_f32_e32 v126, v131, v131
	v_max_f32_e32 v127, 0, v127
	v_max_f32_e32 v128, 0, v128
	v_ashrrev_i32_e32 v135, 31, v134
	v_max_f32_e32 v130, v130, v130
	v_max_f32_e32 v126, 0, v126
	v_mul_f32_e32 v131, v127, v127
	v_max_f32_e32 v127, v132, v132
	v_mul_f32_e32 v132, v128, v128
	v_max_f32_e32 v128, v133, v133
	v_max_f32_e32 v129, v129, v129
	v_lshl_add_u64 v[138:139], s[6:7], 0, v[138:139]
	v_lshlrev_b64 v[140:141], 1, v[134:135]
	v_max_f32_e32 v130, 0, v130
	v_mul_f32_e32 v126, v126, v126
	v_max_f32_e32 v127, 0, v127
	v_max_f32_e32 v128, 0, v128
	v_max_f32_e32 v129, 0, v129
	v_max_f32_e32 v118, v118, v118
	v_lshl_add_u64 v[134:135], v[138:139], 0, v[140:141]
	v_mul_f32_e32 v130, v130, v130
	v_mul_f32_e32 v127, v127, v127
	v_mul_f32_e32 v128, v128, v128
	v_mul_f32_e32 v129, v129, v129
	v_cvt_pk_bf16_f32 v126, v130, v126
	v_max_f32_e32 v118, 0, v118
	v_max_f32_e32 v119, v119, v119
	v_max_f32_e32 v120, v120, v120
	v_cvt_pk_bf16_f32 v127, v127, v128
	v_cvt_pk_bf16_f32 v128, v137, v131
	v_cvt_pk_bf16_f32 v129, v132, v129
	global_store_dwordx4 v[134:135], v[126:129], off nt
	v_max_f32_e32 v119, 0, v119
	v_max_f32_e32 v120, 0, v120
	v_mul_f32_e32 v126, v118, v118
	v_max_f32_e32 v118, v123, v123
	v_max_f32_e32 v122, v122, v122
	v_max_f32_e32 v118, 0, v118
	v_mul_f32_e32 v123, v119, v119
	v_max_f32_e32 v119, v124, v124
	v_mul_f32_e32 v124, v120, v120
	v_max_f32_e32 v120, v125, v125
	v_max_f32_e32 v121, v121, v121
	v_max_f32_e32 v122, 0, v122
	v_mul_f32_e32 v118, v118, v118
	v_max_f32_e32 v119, 0, v119
	v_max_f32_e32 v120, 0, v120
	v_max_f32_e32 v121, 0, v121
	v_mul_f32_e32 v122, v122, v122
	v_mul_f32_e32 v119, v119, v119
	v_mul_f32_e32 v120, v120, v120
	v_mul_f32_e32 v121, v121, v121
	v_cvt_pk_bf16_f32 v118, v122, v118
	v_max_f32_e32 v110, v110, v110
	v_cvt_pk_bf16_f32 v119, v119, v120
	v_cvt_pk_bf16_f32 v120, v126, v123
	v_cvt_pk_bf16_f32 v121, v124, v121
	global_store_dwordx4 v[134:135], v[118:121], off offset:256 nt
	v_max_f32_e32 v110, 0, v110
	v_max_f32_e32 v111, v111, v111
	v_or_b32_e32 v118, 16, v136
	v_max_f32_e32 v112, v112, v112
	v_ashrrev_i32_e32 v119, 31, v118
	v_mul_f32_e32 v120, v110, v110
	v_max_f32_e32 v110, v115, v115
	v_max_f32_e32 v111, 0, v111
	v_max_f32_e32 v112, 0, v112
	v_lshlrev_b64 v[118:119], 14, v[118:119]
	v_max_f32_e32 v114, v114, v114
	v_max_f32_e32 v110, 0, v110
	v_mul_f32_e32 v115, v111, v111
	v_max_f32_e32 v111, v116, v116
	v_mul_f32_e32 v116, v112, v112
	v_max_f32_e32 v112, v117, v117
	v_max_f32_e32 v113, v113, v113
	v_lshl_add_u64 v[118:119], s[6:7], 0, v[118:119]
	v_max_f32_e32 v114, 0, v114
	v_mul_f32_e32 v110, v110, v110
	v_max_f32_e32 v111, 0, v111
	v_max_f32_e32 v112, 0, v112
	v_max_f32_e32 v113, 0, v113
	v_max_f32_e32 v102, v102, v102
	v_lshl_add_u64 v[118:119], v[118:119], 0, v[140:141]
	v_mul_f32_e32 v114, v114, v114
	v_mul_f32_e32 v111, v111, v111
	v_mul_f32_e32 v112, v112, v112
	v_mul_f32_e32 v113, v113, v113
	v_cvt_pk_bf16_f32 v110, v114, v110
	v_max_f32_e32 v102, 0, v102
	v_max_f32_e32 v103, v103, v103
	v_max_f32_e32 v104, v104, v104
	v_cvt_pk_bf16_f32 v111, v111, v112
	v_cvt_pk_bf16_f32 v112, v120, v115
	v_cvt_pk_bf16_f32 v113, v116, v113
	global_store_dwordx4 v[118:119], v[110:113], off nt
	v_max_f32_e32 v103, 0, v103
	v_max_f32_e32 v104, 0, v104
	v_mul_f32_e32 v110, v102, v102
	v_max_f32_e32 v102, v107, v107
	v_max_f32_e32 v106, v106, v106
	v_max_f32_e32 v102, 0, v102
	v_mul_f32_e32 v107, v103, v103
	v_max_f32_e32 v103, v108, v108
	v_mul_f32_e32 v108, v104, v104
	v_max_f32_e32 v104, v109, v109
	v_max_f32_e32 v105, v105, v105
	v_max_f32_e32 v106, 0, v106
	v_mul_f32_e32 v102, v102, v102
	v_max_f32_e32 v103, 0, v103
	v_max_f32_e32 v104, 0, v104
	v_max_f32_e32 v105, 0, v105
	v_mul_f32_e32 v106, v106, v106
	v_mul_f32_e32 v103, v103, v103
	v_mul_f32_e32 v104, v104, v104
	v_mul_f32_e32 v105, v105, v105
	v_cvt_pk_bf16_f32 v102, v106, v102
	v_max_f32_e32 v94, v94, v94
	v_cvt_pk_bf16_f32 v103, v103, v104
	v_cvt_pk_bf16_f32 v104, v110, v107
	v_cvt_pk_bf16_f32 v105, v108, v105
	global_store_dwordx4 v[118:119], v[102:105], off offset:256 nt
	v_max_f32_e32 v94, 0, v94
	v_max_f32_e32 v95, v95, v95
	v_or_b32_e32 v102, 32, v136
	v_max_f32_e32 v96, v96, v96
	v_ashrrev_i32_e32 v103, 31, v102
	v_mul_f32_e32 v104, v94, v94
	v_max_f32_e32 v94, v99, v99
	v_max_f32_e32 v95, 0, v95
	v_max_f32_e32 v96, 0, v96
	v_lshlrev_b64 v[102:103], 14, v[102:103]
	v_max_f32_e32 v98, v98, v98
	v_max_f32_e32 v94, 0, v94
	v_mul_f32_e32 v99, v95, v95
	v_max_f32_e32 v95, v100, v100
	v_mul_f32_e32 v100, v96, v96
	v_max_f32_e32 v96, v101, v101
	v_max_f32_e32 v97, v97, v97
	v_lshl_add_u64 v[102:103], s[6:7], 0, v[102:103]
	v_max_f32_e32 v98, 0, v98
	v_mul_f32_e32 v94, v94, v94
	v_max_f32_e32 v95, 0, v95
	v_max_f32_e32 v96, 0, v96
	v_max_f32_e32 v97, 0, v97
	v_max_f32_e32 v86, v86, v86
	v_lshl_add_u64 v[102:103], v[102:103], 0, v[140:141]
	v_mul_f32_e32 v98, v98, v98
	v_mul_f32_e32 v95, v95, v95
	v_mul_f32_e32 v96, v96, v96
	v_mul_f32_e32 v97, v97, v97
	v_cvt_pk_bf16_f32 v94, v98, v94
	v_max_f32_e32 v86, 0, v86
	v_max_f32_e32 v87, v87, v87
	v_max_f32_e32 v88, v88, v88
	v_cvt_pk_bf16_f32 v95, v95, v96
	v_cvt_pk_bf16_f32 v96, v104, v99
	v_cvt_pk_bf16_f32 v97, v100, v97
	global_store_dwordx4 v[102:103], v[94:97], off nt
	v_max_f32_e32 v87, 0, v87
	v_max_f32_e32 v88, 0, v88
	v_mul_f32_e32 v94, v86, v86
	v_max_f32_e32 v86, v91, v91
	v_max_f32_e32 v90, v90, v90
	v_max_f32_e32 v86, 0, v86
	v_mul_f32_e32 v91, v87, v87
	v_max_f32_e32 v87, v92, v92
	v_mul_f32_e32 v92, v88, v88
	v_max_f32_e32 v88, v93, v93
	v_max_f32_e32 v89, v89, v89
	v_max_f32_e32 v90, 0, v90
	v_mul_f32_e32 v86, v86, v86
	v_max_f32_e32 v87, 0, v87
	v_max_f32_e32 v88, 0, v88
	v_max_f32_e32 v89, 0, v89
	v_mul_f32_e32 v90, v90, v90
	v_mul_f32_e32 v87, v87, v87
	v_mul_f32_e32 v88, v88, v88
	v_mul_f32_e32 v89, v89, v89
	v_cvt_pk_bf16_f32 v86, v90, v86
	v_max_f32_e32 v78, v78, v78
	v_cvt_pk_bf16_f32 v87, v87, v88
	v_cvt_pk_bf16_f32 v88, v94, v91
	v_cvt_pk_bf16_f32 v89, v92, v89
	global_store_dwordx4 v[102:103], v[86:89], off offset:256 nt
	v_max_f32_e32 v78, 0, v78
	v_max_f32_e32 v79, v79, v79
	v_or_b32_e32 v86, 48, v136
	v_max_f32_e32 v80, v80, v80
	v_ashrrev_i32_e32 v87, 31, v86
	v_mul_f32_e32 v88, v78, v78
	v_max_f32_e32 v78, v83, v83
	v_max_f32_e32 v79, 0, v79
	v_max_f32_e32 v80, 0, v80
	v_lshlrev_b64 v[86:87], 14, v[86:87]
	v_max_f32_e32 v82, v82, v82
	v_max_f32_e32 v78, 0, v78
	v_mul_f32_e32 v83, v79, v79
	v_max_f32_e32 v79, v84, v84
	v_mul_f32_e32 v84, v80, v80
	v_max_f32_e32 v80, v85, v85
	v_max_f32_e32 v81, v81, v81
	v_lshl_add_u64 v[86:87], s[6:7], 0, v[86:87]
	v_max_f32_e32 v82, 0, v82
	v_mul_f32_e32 v78, v78, v78
	v_max_f32_e32 v79, 0, v79
	v_max_f32_e32 v80, 0, v80
	v_max_f32_e32 v81, 0, v81
	v_max_f32_e32 v70, v70, v70
	v_max_f32_e32 v71, v71, v71
	v_max_f32_e32 v72, v72, v72
	v_lshl_add_u64 v[86:87], v[86:87], 0, v[140:141]
	v_mul_f32_e32 v82, v82, v82
	v_mul_f32_e32 v79, v79, v79
	v_mul_f32_e32 v80, v80, v80
	v_mul_f32_e32 v81, v81, v81
	v_cvt_pk_bf16_f32 v78, v82, v78
	v_max_f32_e32 v70, 0, v70
	v_max_f32_e32 v71, 0, v71
	v_max_f32_e32 v72, 0, v72
	v_cvt_pk_bf16_f32 v79, v79, v80
	v_cvt_pk_bf16_f32 v80, v88, v83
	v_cvt_pk_bf16_f32 v81, v84, v81
	global_store_dwordx4 v[86:87], v[78:81], off nt
	v_max_f32_e32 v74, v74, v74
	v_max_f32_e32 v73, v73, v73
	v_mul_f32_e32 v78, v70, v70
	v_max_f32_e32 v70, v75, v75
	v_mul_f32_e32 v75, v71, v71
	v_max_f32_e32 v71, v76, v76
	v_mul_f32_e32 v76, v72, v72
	v_max_f32_e32 v72, v77, v77
	v_max_f32_e32 v70, 0, v70
	v_max_f32_e32 v71, 0, v71
	v_max_f32_e32 v72, 0, v72
	v_max_f32_e32 v74, 0, v74
	v_mul_f32_e32 v70, v70, v70
	v_mul_f32_e32 v71, v71, v71
	v_max_f32_e32 v73, 0, v73
	v_mul_f32_e32 v72, v72, v72
	v_max_f32_e32 v62, v62, v62
	v_mul_f32_e32 v74, v74, v74
	v_mul_f32_e32 v73, v73, v73
	v_cvt_pk_bf16_f32 v70, v74, v70
	v_cvt_pk_bf16_f32 v71, v71, v72
	v_cvt_pk_bf16_f32 v72, v78, v75
	v_max_f32_e32 v62, 0, v62
	v_max_f32_e32 v63, v63, v63
	v_max_f32_e32 v64, v64, v64
	v_cvt_pk_bf16_f32 v73, v76, v73
	global_store_dwordx4 v[86:87], v[70:73], off offset:256 nt
	v_max_f32_e32 v66, v66, v66
	v_max_f32_e32 v63, 0, v63
	v_mul_f32_e32 v72, v62, v62
	v_max_f32_e32 v62, v67, v67
	v_max_f32_e32 v64, 0, v64
	v_max_f32_e32 v66, 0, v66
	v_max_f32_e32 v62, 0, v62
	v_mul_f32_e32 v67, v63, v63
	v_max_f32_e32 v63, v68, v68
	v_mul_f32_e32 v68, v64, v64
	v_max_f32_e32 v64, v69, v69
	v_mul_f32_e32 v66, v66, v66
	v_mul_f32_e32 v62, v62, v62
	v_max_f32_e32 v63, 0, v63
	v_max_f32_e32 v64, 0, v64
	v_max_f32_e32 v65, v65, v65
	s_mov_b32 s11, 0x200000
	v_mul_f32_e32 v63, v63, v63
	v_max_f32_e32 v65, 0, v65
	v_mul_f32_e32 v64, v64, v64
	v_cvt_pk_bf16_f32 v62, v66, v62
	v_add_co_u32_e32 v66, vcc, s11, v134
	v_max_f32_e32 v54, v54, v54
	v_max_f32_e32 v55, v55, v55
	v_max_f32_e32 v56, v56, v56
	v_mul_f32_e32 v65, v65, v65
	v_cvt_pk_bf16_f32 v63, v63, v64
	v_cvt_pk_bf16_f32 v64, v72, v67
	v_addc_co_u32_e32 v67, vcc, 0, v135, vcc
	v_max_f32_e32 v54, 0, v54
	v_max_f32_e32 v55, 0, v55
	v_max_f32_e32 v56, 0, v56
	v_cvt_pk_bf16_f32 v65, v68, v65
	global_store_dwordx4 v[66:67], v[62:65], off nt
	v_max_f32_e32 v58, v58, v58
	v_max_f32_e32 v57, v57, v57
	v_mul_f32_e32 v62, v54, v54
	v_max_f32_e32 v54, v59, v59
	v_mul_f32_e32 v59, v55, v55
	v_max_f32_e32 v55, v60, v60
	v_mul_f32_e32 v60, v56, v56
	v_max_f32_e32 v56, v61, v61
	v_max_f32_e32 v54, 0, v54
	v_max_f32_e32 v55, 0, v55
	v_max_f32_e32 v56, 0, v56
	s_mov_b64 s[48:49], 0x200000
	v_max_f32_e32 v58, 0, v58
	v_mul_f32_e32 v54, v54, v54
	v_mul_f32_e32 v55, v55, v55
	v_max_f32_e32 v57, 0, v57
	v_mul_f32_e32 v56, v56, v56
	v_max_f32_e32 v46, v46, v46
	v_lshl_add_u64 v[70:71], v[134:135], 0, s[48:49]
	v_mul_f32_e32 v58, v58, v58
	v_mul_f32_e32 v57, v57, v57
	v_cvt_pk_bf16_f32 v54, v58, v54
	v_cvt_pk_bf16_f32 v55, v55, v56
	v_cvt_pk_bf16_f32 v56, v62, v59
	v_max_f32_e32 v46, 0, v46
	v_max_f32_e32 v47, v47, v47
	v_max_f32_e32 v48, v48, v48
	v_cvt_pk_bf16_f32 v57, v60, v57
	global_store_dwordx4 v[70:71], v[54:57], off offset:256 nt
	v_max_f32_e32 v50, v50, v50
	v_max_f32_e32 v47, 0, v47
	v_mul_f32_e32 v56, v46, v46
	v_max_f32_e32 v46, v51, v51
	v_max_f32_e32 v48, 0, v48
	v_max_f32_e32 v50, 0, v50
	v_max_f32_e32 v46, 0, v46
	v_mul_f32_e32 v51, v47, v47
	v_max_f32_e32 v47, v52, v52
	v_mul_f32_e32 v52, v48, v48
	v_max_f32_e32 v48, v53, v53
	v_mul_f32_e32 v50, v50, v50
	v_mul_f32_e32 v46, v46, v46
	v_max_f32_e32 v47, 0, v47
	v_max_f32_e32 v48, 0, v48
	v_max_f32_e32 v49, v49, v49
	s_mov_b32 s11, 0x240000
	v_mul_f32_e32 v47, v47, v47
	v_max_f32_e32 v49, 0, v49
	v_mul_f32_e32 v48, v48, v48
	v_cvt_pk_bf16_f32 v46, v50, v46
	v_add_co_u32_e32 v50, vcc, s11, v134
	v_max_f32_e32 v38, v38, v38
	v_max_f32_e32 v39, v39, v39
	v_max_f32_e32 v40, v40, v40
	v_mul_f32_e32 v49, v49, v49
	v_cvt_pk_bf16_f32 v47, v47, v48
	v_cvt_pk_bf16_f32 v48, v56, v51
	v_addc_co_u32_e32 v51, vcc, 0, v135, vcc
	v_max_f32_e32 v38, 0, v38
	v_max_f32_e32 v39, 0, v39
	v_max_f32_e32 v40, 0, v40
	v_cvt_pk_bf16_f32 v49, v52, v49
	global_store_dwordx4 v[50:51], v[46:49], off nt
	v_max_f32_e32 v42, v42, v42
	v_max_f32_e32 v41, v41, v41
	v_mul_f32_e32 v46, v38, v38
	v_max_f32_e32 v38, v43, v43
	v_mul_f32_e32 v43, v39, v39
	v_max_f32_e32 v39, v44, v44
	v_mul_f32_e32 v44, v40, v40
	v_max_f32_e32 v40, v45, v45
	v_max_f32_e32 v38, 0, v38
	v_max_f32_e32 v39, 0, v39
	v_max_f32_e32 v40, 0, v40
	s_mov_b64 s[48:49], 0x240000
	v_max_f32_e32 v42, 0, v42
	v_mul_f32_e32 v38, v38, v38
	v_mul_f32_e32 v39, v39, v39
	v_max_f32_e32 v41, 0, v41
	v_mul_f32_e32 v40, v40, v40
	v_max_f32_e32 v30, v30, v30
	v_lshl_add_u64 v[54:55], v[134:135], 0, s[48:49]
	v_mul_f32_e32 v42, v42, v42
	v_mul_f32_e32 v41, v41, v41
	v_cvt_pk_bf16_f32 v38, v42, v38
	v_cvt_pk_bf16_f32 v39, v39, v40
	v_cvt_pk_bf16_f32 v40, v46, v43
	v_max_f32_e32 v30, 0, v30
	v_max_f32_e32 v31, v31, v31
	v_max_f32_e32 v32, v32, v32
	v_cvt_pk_bf16_f32 v41, v44, v41
	global_store_dwordx4 v[54:55], v[38:41], off offset:256 nt
	v_max_f32_e32 v34, v34, v34
	v_max_f32_e32 v31, 0, v31
	v_mul_f32_e32 v40, v30, v30
	v_max_f32_e32 v30, v35, v35
	v_max_f32_e32 v32, 0, v32
	v_max_f32_e32 v34, 0, v34
	v_max_f32_e32 v30, 0, v30
	v_mul_f32_e32 v35, v31, v31
	v_max_f32_e32 v31, v36, v36
	v_mul_f32_e32 v36, v32, v32
	v_max_f32_e32 v32, v37, v37
	v_mul_f32_e32 v34, v34, v34
	v_mul_f32_e32 v30, v30, v30
	v_max_f32_e32 v31, 0, v31
	v_max_f32_e32 v32, 0, v32
	v_max_f32_e32 v33, v33, v33
	s_mov_b32 s11, 0x280000
	v_mul_f32_e32 v31, v31, v31
	v_max_f32_e32 v33, 0, v33
	v_mul_f32_e32 v32, v32, v32
	v_cvt_pk_bf16_f32 v30, v34, v30
	v_add_co_u32_e32 v34, vcc, s11, v134
	v_max_f32_e32 v22, v22, v22
	v_max_f32_e32 v23, v23, v23
	v_max_f32_e32 v24, v24, v24
	v_mul_f32_e32 v33, v33, v33
	v_cvt_pk_bf16_f32 v31, v31, v32
	v_cvt_pk_bf16_f32 v32, v40, v35
	v_addc_co_u32_e32 v35, vcc, 0, v135, vcc
	v_max_f32_e32 v22, 0, v22
	v_max_f32_e32 v23, 0, v23
	v_max_f32_e32 v24, 0, v24
	v_cvt_pk_bf16_f32 v33, v36, v33
	global_store_dwordx4 v[34:35], v[30:33], off nt
	v_max_f32_e32 v26, v26, v26
	v_max_f32_e32 v25, v25, v25
	v_mul_f32_e32 v30, v22, v22
	v_max_f32_e32 v22, v27, v27
	v_mul_f32_e32 v27, v23, v23
	v_max_f32_e32 v23, v28, v28
	v_mul_f32_e32 v28, v24, v24
	v_max_f32_e32 v24, v29, v29
	v_max_f32_e32 v22, 0, v22
	v_max_f32_e32 v23, 0, v23
	v_max_f32_e32 v24, 0, v24
	s_mov_b64 s[48:49], 0x280000
	v_max_f32_e32 v26, 0, v26
	v_mul_f32_e32 v22, v22, v22
	v_mul_f32_e32 v23, v23, v23
	v_max_f32_e32 v25, 0, v25
	v_mul_f32_e32 v24, v24, v24
	v_max_f32_e32 v10, v10, v10
	v_lshl_add_u64 v[38:39], v[134:135], 0, s[48:49]
	v_mul_f32_e32 v26, v26, v26
	v_mul_f32_e32 v25, v25, v25
	v_cvt_pk_bf16_f32 v22, v26, v22
	v_cvt_pk_bf16_f32 v23, v23, v24
	v_cvt_pk_bf16_f32 v24, v30, v27
	v_max_f32_e32 v10, 0, v10
	v_max_f32_e32 v11, v11, v11
	v_max_f32_e32 v12, v12, v12
	v_cvt_pk_bf16_f32 v25, v28, v25
	global_store_dwordx4 v[38:39], v[22:25], off offset:256 nt
	v_max_f32_e32 v18, v18, v18
	v_max_f32_e32 v11, 0, v11
	v_mul_f32_e32 v24, v10, v10
	v_max_f32_e32 v10, v19, v19
	v_max_f32_e32 v12, 0, v12
	v_max_f32_e32 v18, 0, v18
	v_max_f32_e32 v10, 0, v10
	v_mul_f32_e32 v19, v11, v11
	v_max_f32_e32 v11, v20, v20
	v_mul_f32_e32 v20, v12, v12
	v_max_f32_e32 v12, v21, v21
	v_mul_f32_e32 v18, v18, v18
	v_mul_f32_e32 v10, v10, v10
	v_max_f32_e32 v11, 0, v11
	v_max_f32_e32 v12, 0, v12
	v_max_f32_e32 v13, v13, v13
	s_mov_b32 s11, 0x2c0000
	v_mul_f32_e32 v11, v11, v11
	v_max_f32_e32 v13, 0, v13
	v_mul_f32_e32 v12, v12, v12
	v_cvt_pk_bf16_f32 v10, v18, v10
	v_add_co_u32_e32 v18, vcc, s11, v134
	v_max_f32_e32 v2, v2, v2
	v_max_f32_e32 v3, v3, v3
	v_max_f32_e32 v4, v4, v4
	v_mul_f32_e32 v13, v13, v13
	v_cvt_pk_bf16_f32 v11, v11, v12
	v_cvt_pk_bf16_f32 v12, v24, v19
	v_addc_co_u32_e32 v19, vcc, 0, v135, vcc
	v_max_f32_e32 v2, 0, v2
	v_max_f32_e32 v3, 0, v3
	v_max_f32_e32 v4, 0, v4
	v_cvt_pk_bf16_f32 v13, v20, v13
	global_store_dwordx4 v[18:19], v[10:13], off nt
	v_max_f32_e32 v5, v5, v5
	s_mov_b64 s[48:49], 0x2c0000
	v_mul_f32_e32 v10, v2, v2
	v_max_f32_e32 v2, v7, v7
	v_mul_f32_e32 v7, v3, v3
	v_max_f32_e32 v3, v8, v8
	v_mul_f32_e32 v8, v4, v4
	v_max_f32_e32 v4, v9, v9
	v_max_f32_e32 v6, v6, v6
	v_max_f32_e32 v2, 0, v2
	v_max_f32_e32 v3, 0, v3
	v_max_f32_e32 v4, 0, v4
	v_max_f32_e32 v5, 0, v5
	v_lshl_add_u64 v[22:23], v[134:135], 0, s[48:49]
	v_max_f32_e32 v6, 0, v6
	v_mul_f32_e32 v2, v2, v2
	v_mul_f32_e32 v3, v3, v3
	v_mul_f32_e32 v4, v4, v4
	v_mul_f32_e32 v5, v5, v5
	s_andn2_b64 vcc, exec, s[40:41]
	s_mov_b64 s[40:41], -1
	v_mul_f32_e32 v6, v6, v6
	v_cvt_pk_bf16_f32 v2, v6, v2
	v_cvt_pk_bf16_f32 v3, v3, v4
	v_cvt_pk_bf16_f32 v4, v10, v7
	v_cvt_pk_bf16_f32 v5, v8, v5
	global_store_dwordx4 v[22:23], v[2:5], off offset:256 nt
	s_cbranch_vccnz .LBB0_1523
	s_andn2_b64 vcc, exec, s[4:5]
	s_cbranch_vccnz .LBB0_1522
	s_barrier
	s_branch .LBB0_1522
